# v32 stack + P2b next-row prefetch (loads for row r+256 issued at loop top into spare regs, copied at next top)
# speedup vs baseline: 1.0101x; 1.0008x over previous
; __device__ __forceinline__ int opaque_tid() { int t = threadIdx.x; asm volatile("" : "+v"(t)); return t; }
; __device__ __forceinline__ void p2b_rows(const Params& P, int G) {
;     const int tid = opaque_tid(), lane = tid & 63, wave = tid >> 6;
;     const bf16_t* Z = (const bf16_t*)P.out; bf16_t* CQN = (bf16_t*)(P.ws + WS_CQN); bf16_t* CKVN = (bf16_t*)(P.ws + WS_CKVN);
;     const float* cs = (const float*)(P.ws + WS_CS); bf16_t* KR = (bf16_t*)(P.ws + WS_KROPE);
;     for (int m = blockIdx.x * 8 + wave; m < M; m += G * 8) {
;         const bf16_t* zr = Z + (size_t)m * ZC;
;         const u32x4 a = *(const u32x4*)(zr + ZO_CQ + 8 * lane); const u32x2 k = *(const u32x2*)(zr + ZO_CKV + 4 * lane);
.Lgbar_end_2:
.LBB0_297:
	s_or_b64 exec, exec, s[0:1]
	v_mov_b32_e32 v1, v168
	s_waitcnt lgkmcnt(0)
	s_barrier
	s_and_b32 s1, s2, 7
	s_lshl_b32 s1, s1, 11
	s_lshr_b32 s0, s2, 3
	s_lshl_b32 s0, s0, 3
	s_add_i32 s0, s0, s1
	s_lshl_b32 s1, s2, 3
	s_cmpk_eq_u32 s92, 0x100
	s_cselect_b32 s0, s0, s1
	v_ashrrev_i32_e32 v0, 6, v1
	s_nop 0
	v_add_u32_e32 v0, s0, v0
	s_movk_i32 s0, 0x4000
	v_cmp_gt_i32_e32 vcc, s0, v0
	s_and_saveexec_b64 s[22:23], vcc
	s_cbranch_execz .LBB0_302
	v_and_b32_e32 v12, 63, v1
	v_mbcnt_hi_u32_b32 v1, -1, v208
	v_and_b32_e32 v4, 64, v1
	v_add_u32_e32 v4, 64, v4
	v_xor_b32_e32 v5, 1, v1
	v_cmp_lt_i32_e32 vcc, v5, v4
	v_lshlrev_b32_e32 v2, 3, v12
	v_cmp_gt_u32_e64 s[0:1], 32, v12
	v_cndmask_b32_e32 v5, v1, v5, vcc
	v_lshlrev_b32_e32 v19, 2, v5
	v_xor_b32_e32 v5, 2, v1
	v_cmp_lt_i32_e32 vcc, v5, v4
	v_mov_b32_e32 v3, 0
	s_cmpk_eq_u32 s92, 0x100
	s_cselect_b32 s42, 0x100, s42
	s_ashr_i32 s43, s42, 31
	v_cndmask_b32_e32 v5, v1, v5, vcc
	v_lshlrev_b32_e32 v20, 2, v5
	v_xor_b32_e32 v5, 4, v1
	v_cmp_lt_i32_e32 vcc, v5, v4
	s_mov_b64 s[36:37], 0x19800000
	s_mov_b64 s[38:39], 0x18800000
	v_cndmask_b32_e32 v5, v1, v5, vcc
	v_lshlrev_b32_e32 v21, 2, v5
	v_xor_b32_e32 v5, 8, v1
	v_cmp_lt_i32_e32 vcc, v5, v4
	s_mov_b32 s52, 0x3b800000
	s_lshl_b64 s[24:25], s[42:43], 8
	v_cndmask_b32_e32 v5, v1, v5, vcc
	v_lshlrev_b32_e32 v22, 2, v5
	v_xor_b32_e32 v5, 16, v1
	v_cmp_lt_i32_e32 vcc, v5, v4
	s_lshl_b64 s[26:27], s[42:43], 7
	v_mov_b32_e32 v13, v3
	v_cndmask_b32_e32 v5, v1, v5, vcc
	v_lshlrev_b32_e32 v23, 2, v5
	v_xor_b32_e32 v5, 32, v1
	v_cmp_lt_i32_e32 vcc, v5, v4
	v_lshlrev_b32_e32 v4, 1, v12
	v_lshlrev_b32_e32 v12, 4, v12
	v_cndmask_b32_e32 v1, v1, v5, vcc
	v_lshlrev_b32_e32 v24, 2, v1
	v_ashrrev_i32_e32 v1, 31, v0
	v_lshlrev_b64 v[10:11], 9, v[0:1]
	v_lshlrev_b64 v[14:15], 10, v[0:1]
	v_lshlrev_b64 v[6:7], 8, v[0:1]
	v_lshlrev_b64 v[8:9], 7, v[0:1]
	v_or_b32_e32 v10, v10, v2
	v_or_b32_e32 v14, v14, v12
	v_lshlrev_b64 v[16:17], 13, v[0:1]
	v_mov_b32_e32 v5, v3
	v_lshl_add_u64 v[6:7], v[6:7], 0, v[2:3]
	v_or_b32_e32 v8, v8, v4
	v_lshl_add_u64 v[10:11], v[10:11], 0, s[36:37]
	s_lshl_b64 s[36:37], s[42:43], 9
	v_lshl_add_u64 v[14:15], v[14:15], 0, s[38:39]
	s_lshl_b64 s[40:41], s[42:43], 10
	v_lshl_add_u64 v[16:17], s[56:57], 0, v[16:17]
	s_lshl_b64 s[44:45], s[42:43], 13
	s_mov_b64 s[50:51], 0
	s_mov_b32 s53, 0x3b000000
	v_mov_b32_e32 v18, 0x358637bd
	s_mov_b32 s3, 0x800000
	s_movk_i32 s33, 0x7fff
	v_lshl_add_u64 v[120:121], v[16:17], 0, v[12:13]
	v_lshl_add_u64 v[122:123], v[16:17], 0, v[2:3]
	v_lshl_add_u64 v[100:101], v[16:17], 0, v[4:5]
	s_mov_b64 s[4:5], 0x1000
	v_lshl_add_u64 v[102:103], s[58:59], 0, v[6:7]
	global_load_dwordx4 v[108:111], v[120:121], off
	v_lshl_add_u64 v[100:101], v[100:101], 0, s[4:5]
	s_mov_b64 s[4:5], 0x300000
	global_load_dwordx2 v[112:113], v[122:123], off offset:1024
	global_load_ushort v114, v[100:101], off offset:3584
	global_load_ushort v115, v[100:101], off offset:3648
	v_lshl_add_u64 v[102:103], v[102:103], 0, s[4:5]
	global_load_dwordx2 v[116:117], v[102:103], off
	v_lshl_add_u64 v[16:17], v[16:17], 0, s[44:45]
	v_lshl_add_u64 v[6:7], v[6:7], 0, s[24:25]
	s_waitcnt vmcnt(0)
	s_branch .LBB0_300
.LBB0_299:
	s_or_b64 exec, exec, s[38:39]
	v_add_u32_e32 v0, s42, v0
	s_and_b32 s38, s2, 7
	s_lshl_b32 s38, s38, 11
	s_addk_i32 s38, 0x7ff
	s_cmpk_eq_u32 s92, 0x100
	s_cselect_b32 s38, s38, 0x3fff
	v_cmp_lt_i32_e32 vcc, s38, v0
	v_lshl_add_u64 v[8:9], v[8:9], 0, s[26:27]
	v_lshl_add_u64 v[10:11], v[10:11], 0, s[36:37]
	v_lshl_add_u64 v[14:15], v[14:15], 0, s[40:41]
	s_or_b64 s[50:51], vcc, s[50:51]
	s_andn2_b64 exec, exec, s[50:51]
	s_cbranch_execz .LBB0_302
; __device__ __forceinline__ float bf2f(unsigned short u) { return __uint_as_float((unsigned)u << 16); }
; __device__ __forceinline__ unsigned short f2bf(float f) { unsigned u = __float_as_uint(f); return (unsigned short)((u + 0x7fffu + ((u >> 16) & 1u)) >> 16); }
; __device__ __forceinline__ unsigned pk2(float lo, float hi) { return pg8::cvtpk(lo, hi); }
; __device__ __forceinline__ void p2b_rows(const Params& P, int G) {
;     ...
;     for (int m = blockIdx.x * 8 + wave; m < M; m += G * 8) {
;         const bf16_t* zr = Z + (size_t)m * ZC;
;         const u32x4 a = *(const u32x4*)(zr + ZO_CQ + 8 * lane); const u32x2 k = *(const u32x2*)(zr + ZO_CKV + 4 * lane);
;         float s1 = 0.f, s2 = 0.f;
; #pragma unroll
;         for (int e = 0; e < 4; ++e) { const float lo = __uint_as_float(a[e] << 16), hi = __uint_as_float(a[e] & 0xffff0000u); s1 += lo * lo + hi * hi; }
; #pragma unroll
;         for (int e = 0; e < 2; ++e) { const float lo = __uint_as_float(k[e] << 16), hi = __uint_as_float(k[e] & 0xffff0000u); s2 += lo * lo + hi * hi; }
;         s1 = wave_sum(s1); s2 = wave_sum(s2);
;         const float r1 = rsqrtf(s1 * (1.0f / 512.0f) + RMS_EPS), r2 = rsqrtf(s2 * (1.0f / 256.0f) + RMS_EPS);
;         { u32x4 w;
; #pragma unroll
;           for (int e = 0; e < 4; ++e) w[e] = pk2(__uint_as_float(a[e] << 16) * r1, __uint_as_float(a[e] & 0xffff0000u) * r1);
;           *(u32x4*)(CQN + (size_t)m * 512 + 8 * lane) = w;
;           u32x2 w2;
; #pragma unroll
;           for (int e = 0; e < 2; ++e) w2[e] = pk2(__uint_as_float(k[e] << 16) * r2, __uint_as_float(k[e] & 0xffff0000u) * r2);
;           *(u32x2*)(CKVN + (size_t)m * 256 + 4 * lane) = w2; }
;         if (lane < 32) { const float x1 = bf2f(zr[ZO_KR + lane]), x2 = bf2f(zr[ZO_KR + 32 + lane]); const float c = cs[(size_t)m * 64 + 2 * lane], s = cs[(size_t)m * 64 + 2 * lane + 1];
;             KR[(size_t)m * 64 + lane] = f2bf(x1 * c - x2 * s); KR[(size_t)m * 64 + 32 + lane] = f2bf(x2 * c + x1 * s); }
.LBB0_300:
	s_waitcnt vmcnt(4)
	v_mov_b32_e32 v26, v108
	v_mov_b32_e32 v27, v109
	v_mov_b32_e32 v28, v110
	v_mov_b32_e32 v29, v111
	v_mov_b32_e32 v30, v112
	v_mov_b32_e32 v31, v113
	v_mov_b32_e32 v104, v114
	v_mov_b32_e32 v105, v115
	v_mov_b32_e32 v106, v116
	v_mov_b32_e32 v107, v117
	v_add_u32_e32 v118, s42, v0
	s_and_b32 s4, s2, 7
	s_lshl_b32 s4, s4, 11
	s_addk_i32 s4, 0x7ff
	s_cmpk_eq_u32 s92, 0x100
	s_cselect_b32 s4, s4, 0x3fff
	v_cmp_ge_i32_e32 vcc, s4, v118
	s_and_saveexec_b64 s[6:7], vcc
	v_lshl_add_u64 v[120:121], v[16:17], 0, v[12:13]
	v_lshl_add_u64 v[122:123], v[16:17], 0, v[2:3]
	v_lshl_add_u64 v[100:101], v[16:17], 0, v[4:5]
	s_mov_b64 s[4:5], 0x1000
	v_lshl_add_u64 v[102:103], s[58:59], 0, v[6:7]
	global_load_dwordx4 v[108:111], v[120:121], off
	v_lshl_add_u64 v[100:101], v[100:101], 0, s[4:5]
	s_mov_b64 s[4:5], 0x300000
	global_load_dwordx2 v[112:113], v[122:123], off offset:1024
	global_load_ushort v114, v[100:101], off offset:3584
	global_load_ushort v115, v[100:101], off offset:3648
	v_lshl_add_u64 v[102:103], v[102:103], 0, s[4:5]
	global_load_dwordx2 v[116:117], v[102:103], off
	s_or_b64 exec, exec, s[6:7]
	v_lshl_add_u64 v[16:17], v[16:17], 0, s[44:45]
	v_lshl_add_u64 v[6:7], v[6:7], 0, s[24:25]
	v_and_b32_e32 v33, 0xffff0000, v29
	v_and_b32_e32 v35, 0xffff0000, v28
	v_lshlrev_b32_e32 v32, 16, v29
	v_lshlrev_b32_e32 v34, 16, v28
	v_mov_b32_e32 v36, v33
	v_mov_b32_e32 v37, v35
	v_mov_b32_e32 v28, v32
	v_mov_b32_e32 v29, v34
	v_pk_mul_f32 v[36:37], v[36:37], v[36:37]
	v_and_b32_e32 v39, 0xffff0000, v26
	v_pk_fma_f32 v[28:29], v[28:29], v[28:29], v[36:37]
	v_and_b32_e32 v37, 0xffff0000, v27
	v_lshlrev_b32_e32 v36, 16, v27
	v_lshlrev_b32_e32 v38, 16, v26
	v_mov_b32_e32 v26, v39
	v_mov_b32_e32 v27, v37
	v_pk_mul_f32 v[26:27], v[26:27], v[26:27]
	v_mov_b32_e32 v40, v38
	v_mov_b32_e32 v41, v36
	v_and_b32_e32 v43, 0xffff0000, v31
	v_and_b32_e32 v45, 0xffff0000, v30
	v_pk_fma_f32 v[26:27], v[40:41], v[40:41], v[26:27]
	v_lshlrev_b32_e32 v42, 16, v31
	v_lshlrev_b32_e32 v44, 16, v30
	v_mov_b32_e32 v46, v45
	v_mov_b32_e32 v47, v43
	v_add_f32_e32 v26, v26, v27
	v_mov_b32_e32 v30, v44
	v_mov_b32_e32 v31, v42
	v_pk_mul_f32 v[46:47], v[46:47], v[46:47]
	v_pk_add_f32 v[26:27], v[28:29], v[26:27] op_sel_hi:[1,0]
	v_pk_fma_f32 v[30:31], v[30:31], v[30:31], v[46:47]
	v_mov_b32_e32 v47, v28
	v_mov_b32_e32 v46, v30
	v_mov_b32_e32 v26, v31
	v_pk_add_f32 v[26:27], v[46:47], v[26:27]
	s_nop 1
	v_add_f32_dpp v26, v26, v26 quad_perm:[1,0,3,2] row_mask:0xf bank_mask:0xf
	v_add_f32_dpp v27, v27, v27 quad_perm:[1,0,3,2] row_mask:0xf bank_mask:0xf
	v_lshl_add_u64 v[40:41], s[58:59], 0, v[14:15]
	s_nop 1
	v_add_f32_dpp v26, v26, v26 quad_perm:[2,3,0,1] row_mask:0xf bank_mask:0xf
	v_add_f32_dpp v27, v27, v27 quad_perm:[2,3,0,1] row_mask:0xf bank_mask:0xf
	s_nop 1
	v_add_f32_dpp v26, v26, v26 row_half_mirror row_mask:0xf bank_mask:0xf
	v_add_f32_dpp v27, v27, v27 row_half_mirror row_mask:0xf bank_mask:0xf
	s_nop 1
	v_add_f32_dpp v26, v26, v26 row_mirror row_mask:0xf bank_mask:0xf
	v_add_f32_dpp v27, v27, v27 row_mirror row_mask:0xf bank_mask:0xf
	v_mov_b32_e32 v28, v26
	v_mov_b32_e32 v29, v27
	s_nop 1
	v_permlane16_swap_b32_e32 v28, v26
	v_permlane16_swap_b32_e32 v29, v27
	v_pk_add_f32 v[26:27], v[26:27], v[28:29]
	v_mov_b32_e32 v28, v26
	v_mov_b32_e32 v29, v27
	s_nop 1
	v_permlane32_swap_b32_e32 v28, v26
	v_permlane32_swap_b32_e32 v29, v27
	v_pk_add_f32 v[26:27], v[26:27], v[28:29]
	s_waitcnt lgkmcnt(0)
	s_nop 0
	v_pk_fma_f32 v[30:31], v[26:27], s[52:53], v[18:19] op_sel_hi:[1,1,0]
	s_nop 0
	v_mul_f32_e32 v1, 0x4b800000, v31
	v_cmp_gt_f32_e64 s[38:39], s3, v31
	v_cmp_gt_f32_e32 vcc, s3, v30
	s_nop 0
	v_cndmask_b32_e64 v1, v31, v1, s[38:39]
	v_rsq_f32_e32 v1, v1
	s_nop 0
	v_mul_f32_e32 v25, 0x45800000, v1
	v_cndmask_b32_e64 v46, v1, v25, s[38:39]
	v_mul_f32_e32 v1, 0x4b800000, v30
	v_cndmask_b32_e32 v1, v30, v1, vcc
	v_rsq_f32_e32 v1, v1
	v_pk_mul_f32 v[26:27], v[46:47], v[38:39] op_sel_hi:[0,1]
	v_pk_mul_f32 v[28:29], v[46:47], v[36:37] op_sel_hi:[0,1]
	v_cvt_pk_bf16_f32 v26, v26, v27
	v_cvt_pk_bf16_f32 v27, v28, v29
	v_pk_mul_f32 v[28:29], v[46:47], v[34:35] op_sel_hi:[0,1]
	v_pk_mul_f32 v[32:33], v[46:47], v[32:33] op_sel_hi:[0,1]
	v_cvt_pk_bf16_f32 v28, v28, v29
	v_cvt_pk_bf16_f32 v29, v32, v33
	v_mul_f32_e32 v25, 0x45800000, v1
	global_store_dwordx4 v[40:41], v[26:29], off
	s_nop 1
	v_cndmask_b32_e32 v26, v1, v25, vcc
	v_pk_mul_f32 v[28:29], v[26:27], v[44:45] op_sel_hi:[0,1]
	v_pk_mul_f32 v[26:27], v[26:27], v[42:43] op_sel_hi:[0,1]
	v_cvt_pk_bf16_f32 v28, v28, v29
	v_cvt_pk_bf16_f32 v29, v26, v27
	v_lshl_add_u64 v[26:27], s[58:59], 0, v[10:11]
	global_store_dwordx2 v[26:27], v[28:29], off
	s_and_saveexec_b64 s[38:39], s[0:1]
	s_cbranch_execz .LBB0_299
	v_lshl_add_u64 v[28:29], s[58:59], 0, v[8:9]
	v_lshlrev_b32_e32 v1, 16, v104
	v_lshlrev_b32_e32 v25, 16, v105
	v_mov_b32_e32 v26, v106
	v_mov_b32_e32 v27, v107
	v_add_co_u32_e32 v28, vcc, 0x700000, v28
	v_mul_f32_e32 v30, v27, v25
	v_mul_f32_e32 v25, v26, v25
	v_fma_f32 v26, v26, v1, -v30
	v_fmac_f32_e32 v25, v27, v1
	v_bfe_u32 v1, v26, 16, 1
	v_addc_co_u32_e32 v29, vcc, 0, v29, vcc
	v_bfe_u32 v27, v25, 16, 1
	v_add3_u32 v1, v26, v1, s33
	v_add3_u32 v25, v25, v27, s33
	global_store_short_d16_hi v[28:29], v1, off
	global_store_short_d16_hi v[28:29], v25, off offset:64
	s_branch .LBB0_299
